# beta/alpha MFMA GEMV with LDS-staged weights: activation prefetch ring deepened from 4 to 8 K-blocks
# speedup vs baseline: 1.0086x; 1.0031x over previous
; __device__ __forceinline__ float bf2f(bfu h) { return __uint_as_float(((unsigned)h) << 16); }
; #define SHX(v, m) shx_((v), (m), lane)
; __device__ __forceinline__ int ptid_(int wave) { int l_; asm volatile("v_mbcnt_lo_u32_b32 %0, -1, 0\n\tv_mbcnt_hi_u32_b32 %0, -1, %0" : "=v"(l_)); return (wave << 6) | l_; }
; __device__ void ba_item(const Params& p, int L, int rp) {
;     ...
;   int tid = ptid_(p.tid); asm volatile("" : "+v"(tid));
;   const int wid = tid >> 6, lane = tid & 63;
;   f32x4 wr_[8][4];
;   _Pragma("unroll") for (int j = 0; j < 8; ++j) _Pragma("unroll") for (int e4 = 0; e4 < 4; ++e4)
;     wr_[j][e4] = *(const f32x4*)(wba + j * 1024 + lane * 16 + e4 * 4);
;   for (int bt = 0; bt < 8; ++bt) {
;     bf16x8 h0[2], h1[2]; f32x4 ps[2][4];
;     _Pragma("unroll") for (int u = 0; u < 2; ++u) {
;       const int row = rp * 128 + wid * 16 + bt * 2 + u;
;       const bfu* hr = hb + (long)row * 1024 + lane * 16;
;       h0[u] = *(const bf16x8*)hr; h1[u] = *(const bf16x8*)(hr + 8);
;       _Pragma("unroll") for (int i = 0; i < 4; ++i) ps[u][i] = *(const f32x4*)(rowss + (long)row * 16 + i * 4);
;     }
;     _Pragma("unroll") for (int u = 0; u < 2; ++u) {
;       const int row = rp * 128 + wid * 16 + bt * 2 + u;
;       float hf[16];
;       _Pragma("unroll") for (int e = 0; e < 8; ++e) { hf[e] = bf2f((bfu)h0[u][e]); hf[8 + e] = bf2f((bfu)h1[u][e]); }
;       float a[8];
;       _Pragma("unroll") for (int j = 0; j < 8; ++j) {
;         float s = 0.f;
;         _Pragma("unroll") for (int e4 = 0; e4 < 4; ++e4) _Pragma("unroll") for (int e = 0; e < 4; ++e) s += hf[e4 * 4 + e] * wr_[j][e4][e];
;         _Pragma("unroll") for (int o = 32; o >= 1; o >>= 1) s += SHX(s, o);
.LBB0_612:
	s_cmpk_gt_i32 s18, 0x6ff
	s_mov_b64 s[0:1], -1
	s_cbranch_scc0 .LBB0_628
	v_mbcnt_lo_u32_b32 v0, -1, 0
	v_mbcnt_hi_u32_b32 v0, -1, v0
	s_waitcnt vmcnt(0) lgkmcnt(0)
	s_barrier
	v_readlane_b32 s24, v254, 62
	v_readlane_b32 s25, v254, 63
	s_lshr_b32 s2, s33, 2
	s_add_i32 s2, s2, s20
	s_add_i32 s2, s2, 0xfffc8000
	v_and_b32_e32 v2, 15, v0
	v_lshrrev_b32_e32 v3, 4, v0
	v_or_b32_e32 v144, s33, v0
	v_lshlrev_b32_e32 v150, 4, v144
	global_load_dwordx4 v[152:155], v150, s[26:27]
	v_add_u32_e32 v150, 0x2000, v150
	global_load_dwordx4 v[156:159], v150, s[26:27]
	v_add_u32_e32 v150, 0x2000, v150
	global_load_dwordx4 v[160:163], v150, s[26:27]
	v_add_u32_e32 v150, 0x2000, v150
	global_load_dwordx4 v[164:167], v150, s[26:27]
	v_and_b32_e32 v145, 0xff, v144
	v_lshrrev_b32_e32 v149, 3, v145
	v_lshlrev_b32_e32 v149, 10, v149
	v_bfe_u32 v146, v144, 1, 2
	v_lshl_or_b32 v149, v146, 8, v149
	v_lshrrev_b32_e32 v146, 8, v144
	v_lshl_or_b32 v149, v146, 5, v149
	v_and_b32_e32 v146, 1, v144
	v_lshl_or_b32 v149, v146, 4, v149
	v_add_u32_e32 v144, s2, v2
	v_lshlrev_b32_e32 v144, 11, v144
	v_lshl_add_u32 v144, v3, 4, v144
	v_mov_b32_e32 v145, 0
	v_lshl_add_u64 v[4:5], s[80:81], 0, v[144:145]
	v_and_b32_e32 v138, 7, v2
	v_lshlrev_b32_e32 v148, 5, v138
	v_lshl_or_b32 v148, v3, 8, v148
	v_lshl_add_u32 v144, v3, 2, s2
	v_lshlrev_b32_e32 v144, 6, v144
	v_lshl_add_u64 v[136:137], s[24:25], 0, v[144:145]
	v_max_u32_e32 v144, 4, v138
	v_add_u32_e32 v144, s19, v144
	v_lshlrev_b32_e32 v144, 2, v144
	v_readlane_b32 s92, v254, 0
	v_readlane_b32 s93, v254, 1
	v_readlane_b32 s94, v254, 2
	v_readlane_b32 s95, v254, 3
	v_readlane_b32 s0, v252, 18
	v_readlane_b32 s1, v252, 19
	v_lshl_add_u32 v146, v3, 2, s2
	v_lshlrev_b32_e32 v146, 5, v146
	v_lshl_add_u32 v146, v138, 2, v146
	v_mov_b32_e32 v147, 0
	v_lshl_add_u64 v[140:141], s[0:1], 0, v[146:147]
	global_load_dword v142, v144, s[94:95]
	global_load_dword v143, v144, s[92:93]
	global_load_dwordx4 v[72:75], v[136:137], off offset:0
	global_load_dwordx4 v[76:79], v[136:137], off offset:16
	global_load_dwordx4 v[80:83], v[136:137], off offset:32
	global_load_dwordx4 v[84:87], v[136:137], off offset:48
	global_load_dwordx4 v[88:91], v[136:137], off offset:64
	global_load_dwordx4 v[92:95], v[136:137], off offset:80
	global_load_dwordx4 v[96:99], v[136:137], off offset:96
	global_load_dwordx4 v[100:103], v[136:137], off offset:112
	global_load_dwordx4 v[104:107], v[136:137], off offset:128
	global_load_dwordx4 v[108:111], v[136:137], off offset:144
	global_load_dwordx4 v[112:115], v[136:137], off offset:160
	global_load_dwordx4 v[116:119], v[136:137], off offset:176
	global_load_dwordx4 v[120:123], v[136:137], off offset:192
	global_load_dwordx4 v[124:127], v[136:137], off offset:208
	global_load_dwordx4 v[128:131], v[136:137], off offset:224
	global_load_dwordx4 v[132:135], v[136:137], off offset:240
	v_mov_b32_e32 v8, 0
	v_mov_b32_e32 v9, 0
	v_mov_b32_e32 v10, 0
	v_mov_b32_e32 v11, 0
	global_load_dwordx4 v[16:19], v[4:5], off
	global_load_dwordx4 v[20:23], v[4:5], off offset:64
	global_load_dwordx4 v[24:27], v[4:5], off offset:128
	global_load_dwordx4 v[28:31], v[4:5], off offset:192
	global_load_dwordx4 v[32:35], v[4:5], off offset:256
	global_load_dwordx4 v[36:39], v[4:5], off offset:320
	global_load_dwordx4 v[40:43], v[4:5], off offset:384
	global_load_dwordx4 v[44:47], v[4:5], off offset:448
	s_waitcnt vmcnt(26)
	ds_write_b128 v149, v[152:155]
	ds_write_b128 v149, v[156:159] offset:64
	ds_write_b128 v149, v[160:163] offset:128
	ds_write_b128 v149, v[164:167] offset:192
	s_waitcnt lgkmcnt(0)
	s_barrier
	ds_read_b128 v[48:51], v148
	ds_read_b128 v[52:55], v148 offset:16
	ds_read_b128 v[56:59], v148 offset:1024
	ds_read_b128 v[60:63], v148 offset:1040
	s_waitcnt vmcnt(7)
	v_lshlrev_b32_e32 v64, 16, v16
	v_and_b32_e32 v65, 0xffff0000, v16
	v_lshlrev_b32_e32 v66, 16, v17
	v_and_b32_e32 v67, 0xffff0000, v17
	v_lshlrev_b32_e32 v68, 16, v18
	v_and_b32_e32 v69, 0xffff0000, v18
	v_lshlrev_b32_e32 v70, 16, v19
	v_and_b32_e32 v71, 0xffff0000, v19
	s_waitcnt lgkmcnt(2)
	v_mfma_f32_16x16x4_f32 v[8:11], v64, v48, v[8:11]
	v_mfma_f32_16x16x4_f32 v[8:11], v65, v49, v[8:11]
	v_mfma_f32_16x16x4_f32 v[8:11], v66, v50, v[8:11]
	v_mfma_f32_16x16x4_f32 v[8:11], v67, v51, v[8:11]
	v_mfma_f32_16x16x4_f32 v[8:11], v68, v52, v[8:11]
	v_mfma_f32_16x16x4_f32 v[8:11], v69, v53, v[8:11]
	v_mfma_f32_16x16x4_f32 v[8:11], v70, v54, v[8:11]
	v_mfma_f32_16x16x4_f32 v[8:11], v71, v55, v[8:11]
	global_load_dwordx4 v[16:19], v[4:5], off offset:512
	ds_read_b128 v[48:51], v148 offset:2048
	ds_read_b128 v[52:55], v148 offset:2064
	s_waitcnt vmcnt(7)
	v_lshlrev_b32_e32 v64, 16, v20
	v_and_b32_e32 v65, 0xffff0000, v20
	v_lshlrev_b32_e32 v66, 16, v21
	v_and_b32_e32 v67, 0xffff0000, v21
	v_lshlrev_b32_e32 v68, 16, v22
	v_and_b32_e32 v69, 0xffff0000, v22
	v_lshlrev_b32_e32 v70, 16, v23
	v_and_b32_e32 v71, 0xffff0000, v23
	s_waitcnt lgkmcnt(2)
	v_mfma_f32_16x16x4_f32 v[8:11], v64, v56, v[8:11]
	v_mfma_f32_16x16x4_f32 v[8:11], v65, v57, v[8:11]
	v_mfma_f32_16x16x4_f32 v[8:11], v66, v58, v[8:11]
	v_mfma_f32_16x16x4_f32 v[8:11], v67, v59, v[8:11]
	v_mfma_f32_16x16x4_f32 v[8:11], v68, v60, v[8:11]
	v_mfma_f32_16x16x4_f32 v[8:11], v69, v61, v[8:11]
	v_mfma_f32_16x16x4_f32 v[8:11], v70, v62, v[8:11]
	v_mfma_f32_16x16x4_f32 v[8:11], v71, v63, v[8:11]
	global_load_dwordx4 v[20:23], v[4:5], off offset:576
	ds_read_b128 v[56:59], v148 offset:3072
	ds_read_b128 v[60:63], v148 offset:3088
	s_waitcnt vmcnt(7)
	v_lshlrev_b32_e32 v64, 16, v24
	v_and_b32_e32 v65, 0xffff0000, v24
	v_lshlrev_b32_e32 v66, 16, v25
	v_and_b32_e32 v67, 0xffff0000, v25
	v_lshlrev_b32_e32 v68, 16, v26
	v_and_b32_e32 v69, 0xffff0000, v26
	v_lshlrev_b32_e32 v70, 16, v27
	v_and_b32_e32 v71, 0xffff0000, v27
	s_waitcnt lgkmcnt(2)
; #define SHX(v, m) shx_((v), (m), lane)
; __device__ void ba_item(const Params& p, int L, int rp) {
;     ...
;       _Pragma("unroll") for (int j = 0; j < 8; ++j) {
;         float s = 0.f;
;         _Pragma("unroll") for (int e4 = 0; e4 < 4; ++e4) _Pragma("unroll") for (int e = 0; e < 4; ++e) s += hf[e4 * 4 + e] * wr_[j][e4][e];
;         _Pragma("unroll") for (int o = 32; o >= 1; o >>= 1) s += SHX(s, o);
	v_mfma_f32_16x16x4_f32 v[8:11], v64, v48, v[8:11]
	v_mfma_f32_16x16x4_f32 v[8:11], v65, v49, v[8:11]
	v_mfma_f32_16x16x4_f32 v[8:11], v66, v50, v[8:11]
	v_mfma_f32_16x16x4_f32 v[8:11], v67, v51, v[8:11]
	v_mfma_f32_16x16x4_f32 v[8:11], v68, v52, v[8:11]
	v_mfma_f32_16x16x4_f32 v[8:11], v69, v53, v[8:11]
	v_mfma_f32_16x16x4_f32 v[8:11], v70, v54, v[8:11]
	v_mfma_f32_16x16x4_f32 v[8:11], v71, v55, v[8:11]
	global_load_dwordx4 v[24:27], v[4:5], off offset:640
	ds_read_b128 v[48:51], v148 offset:4096
	ds_read_b128 v[52:55], v148 offset:4112
	s_waitcnt vmcnt(7)
	v_lshlrev_b32_e32 v64, 16, v28
	v_and_b32_e32 v65, 0xffff0000, v28
	v_lshlrev_b32_e32 v66, 16, v29
	v_and_b32_e32 v67, 0xffff0000, v29
	v_lshlrev_b32_e32 v68, 16, v30
	v_and_b32_e32 v69, 0xffff0000, v30
	v_lshlrev_b32_e32 v70, 16, v31
	v_and_b32_e32 v71, 0xffff0000, v31
	s_waitcnt lgkmcnt(2)
	v_mfma_f32_16x16x4_f32 v[8:11], v64, v56, v[8:11]
	v_mfma_f32_16x16x4_f32 v[8:11], v65, v57, v[8:11]
	v_mfma_f32_16x16x4_f32 v[8:11], v66, v58, v[8:11]
	v_mfma_f32_16x16x4_f32 v[8:11], v67, v59, v[8:11]
	v_mfma_f32_16x16x4_f32 v[8:11], v68, v60, v[8:11]
	v_mfma_f32_16x16x4_f32 v[8:11], v69, v61, v[8:11]
	v_mfma_f32_16x16x4_f32 v[8:11], v70, v62, v[8:11]
	v_mfma_f32_16x16x4_f32 v[8:11], v71, v63, v[8:11]
	global_load_dwordx4 v[28:31], v[4:5], off offset:704
	ds_read_b128 v[56:59], v148 offset:5120
	ds_read_b128 v[60:63], v148 offset:5136
	s_waitcnt vmcnt(7)
	v_lshlrev_b32_e32 v64, 16, v32
	v_and_b32_e32 v65, 0xffff0000, v32
	v_lshlrev_b32_e32 v66, 16, v33
	v_and_b32_e32 v67, 0xffff0000, v33
	v_lshlrev_b32_e32 v68, 16, v34
	v_and_b32_e32 v69, 0xffff0000, v34
	v_lshlrev_b32_e32 v70, 16, v35
	v_and_b32_e32 v71, 0xffff0000, v35
	s_waitcnt lgkmcnt(2)
	v_mfma_f32_16x16x4_f32 v[8:11], v64, v48, v[8:11]
	v_mfma_f32_16x16x4_f32 v[8:11], v65, v49, v[8:11]
	v_mfma_f32_16x16x4_f32 v[8:11], v66, v50, v[8:11]
	v_mfma_f32_16x16x4_f32 v[8:11], v67, v51, v[8:11]
	v_mfma_f32_16x16x4_f32 v[8:11], v68, v52, v[8:11]
	v_mfma_f32_16x16x4_f32 v[8:11], v69, v53, v[8:11]
	v_mfma_f32_16x16x4_f32 v[8:11], v70, v54, v[8:11]
	v_mfma_f32_16x16x4_f32 v[8:11], v71, v55, v[8:11]
	global_load_dwordx4 v[32:35], v[4:5], off offset:768
	ds_read_b128 v[48:51], v148 offset:6144
	ds_read_b128 v[52:55], v148 offset:6160
	s_waitcnt vmcnt(7)
	v_lshlrev_b32_e32 v64, 16, v36
	v_and_b32_e32 v65, 0xffff0000, v36
	v_lshlrev_b32_e32 v66, 16, v37
	v_and_b32_e32 v67, 0xffff0000, v37
	v_lshlrev_b32_e32 v68, 16, v38
	v_and_b32_e32 v69, 0xffff0000, v38
	v_lshlrev_b32_e32 v70, 16, v39
	v_and_b32_e32 v71, 0xffff0000, v39
	s_waitcnt lgkmcnt(2)
	v_mfma_f32_16x16x4_f32 v[8:11], v64, v56, v[8:11]
	v_mfma_f32_16x16x4_f32 v[8:11], v65, v57, v[8:11]
	v_mfma_f32_16x16x4_f32 v[8:11], v66, v58, v[8:11]
	v_mfma_f32_16x16x4_f32 v[8:11], v67, v59, v[8:11]
	v_mfma_f32_16x16x4_f32 v[8:11], v68, v60, v[8:11]
	v_mfma_f32_16x16x4_f32 v[8:11], v69, v61, v[8:11]
	v_mfma_f32_16x16x4_f32 v[8:11], v70, v62, v[8:11]
	v_mfma_f32_16x16x4_f32 v[8:11], v71, v63, v[8:11]
	global_load_dwordx4 v[36:39], v[4:5], off offset:832
	ds_read_b128 v[56:59], v148 offset:7168
	ds_read_b128 v[60:63], v148 offset:7184
	s_waitcnt vmcnt(7)
	v_lshlrev_b32_e32 v64, 16, v40
	v_and_b32_e32 v65, 0xffff0000, v40
	v_lshlrev_b32_e32 v66, 16, v41
	v_and_b32_e32 v67, 0xffff0000, v41
	v_lshlrev_b32_e32 v68, 16, v42
	v_and_b32_e32 v69, 0xffff0000, v42
	v_lshlrev_b32_e32 v70, 16, v43
	v_and_b32_e32 v71, 0xffff0000, v43
	s_waitcnt lgkmcnt(2)
	v_mfma_f32_16x16x4_f32 v[8:11], v64, v48, v[8:11]
	v_mfma_f32_16x16x4_f32 v[8:11], v65, v49, v[8:11]
	v_mfma_f32_16x16x4_f32 v[8:11], v66, v50, v[8:11]
	v_mfma_f32_16x16x4_f32 v[8:11], v67, v51, v[8:11]
	v_mfma_f32_16x16x4_f32 v[8:11], v68, v52, v[8:11]
	v_mfma_f32_16x16x4_f32 v[8:11], v69, v53, v[8:11]
	v_mfma_f32_16x16x4_f32 v[8:11], v70, v54, v[8:11]
	v_mfma_f32_16x16x4_f32 v[8:11], v71, v55, v[8:11]
	global_load_dwordx4 v[40:43], v[4:5], off offset:896
	ds_read_b128 v[48:51], v148 offset:8192
	ds_read_b128 v[52:55], v148 offset:8208
	s_waitcnt vmcnt(7)
	v_lshlrev_b32_e32 v64, 16, v44
	v_and_b32_e32 v65, 0xffff0000, v44
	v_lshlrev_b32_e32 v66, 16, v45
	v_and_b32_e32 v67, 0xffff0000, v45
	v_lshlrev_b32_e32 v68, 16, v46
	v_and_b32_e32 v69, 0xffff0000, v46
	v_lshlrev_b32_e32 v70, 16, v47
	v_and_b32_e32 v71, 0xffff0000, v47
	s_waitcnt lgkmcnt(2)
	v_mfma_f32_16x16x4_f32 v[8:11], v64, v56, v[8:11]
	v_mfma_f32_16x16x4_f32 v[8:11], v65, v57, v[8:11]
	v_mfma_f32_16x16x4_f32 v[8:11], v66, v58, v[8:11]
	v_mfma_f32_16x16x4_f32 v[8:11], v67, v59, v[8:11]
	v_mfma_f32_16x16x4_f32 v[8:11], v68, v60, v[8:11]
	v_mfma_f32_16x16x4_f32 v[8:11], v69, v61, v[8:11]
	v_mfma_f32_16x16x4_f32 v[8:11], v70, v62, v[8:11]
	v_mfma_f32_16x16x4_f32 v[8:11], v71, v63, v[8:11]
	global_load_dwordx4 v[44:47], v[4:5], off offset:960
	ds_read_b128 v[56:59], v148 offset:9216
	ds_read_b128 v[60:63], v148 offset:9232
	s_waitcnt vmcnt(7)
	v_lshlrev_b32_e32 v64, 16, v16
	v_and_b32_e32 v65, 0xffff0000, v16
	v_lshlrev_b32_e32 v66, 16, v17
	v_and_b32_e32 v67, 0xffff0000, v17
	v_lshlrev_b32_e32 v68, 16, v18
	v_and_b32_e32 v69, 0xffff0000, v18
	v_lshlrev_b32_e32 v70, 16, v19
	v_and_b32_e32 v71, 0xffff0000, v19
	s_waitcnt lgkmcnt(2)
	v_mfma_f32_16x16x4_f32 v[8:11], v64, v48, v[8:11]
	v_mfma_f32_16x16x4_f32 v[8:11], v65, v49, v[8:11]
	v_mfma_f32_16x16x4_f32 v[8:11], v66, v50, v[8:11]
	v_mfma_f32_16x16x4_f32 v[8:11], v67, v51, v[8:11]
	v_mfma_f32_16x16x4_f32 v[8:11], v68, v52, v[8:11]
	v_mfma_f32_16x16x4_f32 v[8:11], v69, v53, v[8:11]
	v_mfma_f32_16x16x4_f32 v[8:11], v70, v54, v[8:11]
	v_mfma_f32_16x16x4_f32 v[8:11], v71, v55, v[8:11]
	global_load_dwordx4 v[16:19], v[4:5], off offset:1024
	ds_read_b128 v[48:51], v148 offset:10240
	ds_read_b128 v[52:55], v148 offset:10256
	s_waitcnt vmcnt(7)
; __device__ __forceinline__ float bf2f(bfu h) { return __uint_as_float(((unsigned)h) << 16); }
; #define SHX(v, m) shx_((v), (m), lane)
; __device__ void ba_item(const Params& p, int L, int rp) {
;     ...
;   for (int bt = 0; bt < 8; ++bt) {
;     bf16x8 h0[2], h1[2]; f32x4 ps[2][4];
;     _Pragma("unroll") for (int u = 0; u < 2; ++u) {
;       const int row = rp * 128 + wid * 16 + bt * 2 + u;
;       const bfu* hr = hb + (long)row * 1024 + lane * 16;
;       h0[u] = *(const bf16x8*)hr; h1[u] = *(const bf16x8*)(hr + 8);
;       _Pragma("unroll") for (int i = 0; i < 4; ++i) ps[u][i] = *(const f32x4*)(rowss + (long)row * 16 + i * 4);
;     }
;     _Pragma("unroll") for (int u = 0; u < 2; ++u) {
;       const int row = rp * 128 + wid * 16 + bt * 2 + u;
;       float hf[16];
;       _Pragma("unroll") for (int e = 0; e < 8; ++e) { hf[e] = bf2f((bfu)h0[u][e]); hf[8 + e] = bf2f((bfu)h1[u][e]); }
;       float a[8];
;       _Pragma("unroll") for (int j = 0; j < 8; ++j) {
;         float s = 0.f;
;         _Pragma("unroll") for (int e4 = 0; e4 < 4; ++e4) _Pragma("unroll") for (int e = 0; e < 4; ++e) s += hf[e4 * 4 + e] * wr_[j][e4][e];
;         _Pragma("unroll") for (int o = 32; o >= 1; o >>= 1) s += SHX(s, o);
;         a[j] = s;
;       }
	v_lshlrev_b32_e32 v64, 16, v20
	v_and_b32_e32 v65, 0xffff0000, v20
	v_lshlrev_b32_e32 v66, 16, v21
	v_and_b32_e32 v67, 0xffff0000, v21
	v_lshlrev_b32_e32 v68, 16, v22
	v_and_b32_e32 v69, 0xffff0000, v22
	v_lshlrev_b32_e32 v70, 16, v23
	v_and_b32_e32 v71, 0xffff0000, v23
	s_waitcnt lgkmcnt(2)
	v_mfma_f32_16x16x4_f32 v[8:11], v64, v56, v[8:11]
	v_mfma_f32_16x16x4_f32 v[8:11], v65, v57, v[8:11]
	v_mfma_f32_16x16x4_f32 v[8:11], v66, v58, v[8:11]
	v_mfma_f32_16x16x4_f32 v[8:11], v67, v59, v[8:11]
	v_mfma_f32_16x16x4_f32 v[8:11], v68, v60, v[8:11]
	v_mfma_f32_16x16x4_f32 v[8:11], v69, v61, v[8:11]
	v_mfma_f32_16x16x4_f32 v[8:11], v70, v62, v[8:11]
	v_mfma_f32_16x16x4_f32 v[8:11], v71, v63, v[8:11]
	global_load_dwordx4 v[20:23], v[4:5], off offset:1088
	ds_read_b128 v[56:59], v148 offset:11264
	ds_read_b128 v[60:63], v148 offset:11280
	s_waitcnt vmcnt(7)
	v_lshlrev_b32_e32 v64, 16, v24
	v_and_b32_e32 v65, 0xffff0000, v24
	v_lshlrev_b32_e32 v66, 16, v25
	v_and_b32_e32 v67, 0xffff0000, v25
	v_lshlrev_b32_e32 v68, 16, v26
	v_and_b32_e32 v69, 0xffff0000, v26
	v_lshlrev_b32_e32 v70, 16, v27
	v_and_b32_e32 v71, 0xffff0000, v27
	s_waitcnt lgkmcnt(2)
	v_mfma_f32_16x16x4_f32 v[8:11], v64, v48, v[8:11]
	v_mfma_f32_16x16x4_f32 v[8:11], v65, v49, v[8:11]
	v_mfma_f32_16x16x4_f32 v[8:11], v66, v50, v[8:11]
	v_mfma_f32_16x16x4_f32 v[8:11], v67, v51, v[8:11]
	v_mfma_f32_16x16x4_f32 v[8:11], v68, v52, v[8:11]
	v_mfma_f32_16x16x4_f32 v[8:11], v69, v53, v[8:11]
	v_mfma_f32_16x16x4_f32 v[8:11], v70, v54, v[8:11]
	v_mfma_f32_16x16x4_f32 v[8:11], v71, v55, v[8:11]
	global_load_dwordx4 v[24:27], v[4:5], off offset:1152
	ds_read_b128 v[48:51], v148 offset:12288
	ds_read_b128 v[52:55], v148 offset:12304
	s_waitcnt vmcnt(7)
	v_lshlrev_b32_e32 v64, 16, v28
	v_and_b32_e32 v65, 0xffff0000, v28
	v_lshlrev_b32_e32 v66, 16, v29
	v_and_b32_e32 v67, 0xffff0000, v29
	v_lshlrev_b32_e32 v68, 16, v30
	v_and_b32_e32 v69, 0xffff0000, v30
	v_lshlrev_b32_e32 v70, 16, v31
	v_and_b32_e32 v71, 0xffff0000, v31
	s_waitcnt lgkmcnt(2)
	v_mfma_f32_16x16x4_f32 v[8:11], v64, v56, v[8:11]
	v_mfma_f32_16x16x4_f32 v[8:11], v65, v57, v[8:11]
	v_mfma_f32_16x16x4_f32 v[8:11], v66, v58, v[8:11]
	v_mfma_f32_16x16x4_f32 v[8:11], v67, v59, v[8:11]
	v_mfma_f32_16x16x4_f32 v[8:11], v68, v60, v[8:11]
	v_mfma_f32_16x16x4_f32 v[8:11], v69, v61, v[8:11]
	v_mfma_f32_16x16x4_f32 v[8:11], v70, v62, v[8:11]
	v_mfma_f32_16x16x4_f32 v[8:11], v71, v63, v[8:11]
	global_load_dwordx4 v[28:31], v[4:5], off offset:1216
	ds_read_b128 v[56:59], v148 offset:13312
	ds_read_b128 v[60:63], v148 offset:13328
	s_waitcnt vmcnt(7)
	v_lshlrev_b32_e32 v64, 16, v32
	v_and_b32_e32 v65, 0xffff0000, v32
	v_lshlrev_b32_e32 v66, 16, v33
	v_and_b32_e32 v67, 0xffff0000, v33
	v_lshlrev_b32_e32 v68, 16, v34
	v_and_b32_e32 v69, 0xffff0000, v34
	v_lshlrev_b32_e32 v70, 16, v35
	v_and_b32_e32 v71, 0xffff0000, v35
	s_waitcnt lgkmcnt(2)
	v_mfma_f32_16x16x4_f32 v[8:11], v64, v48, v[8:11]
	v_mfma_f32_16x16x4_f32 v[8:11], v65, v49, v[8:11]
	v_mfma_f32_16x16x4_f32 v[8:11], v66, v50, v[8:11]
	v_mfma_f32_16x16x4_f32 v[8:11], v67, v51, v[8:11]
	v_mfma_f32_16x16x4_f32 v[8:11], v68, v52, v[8:11]
	v_mfma_f32_16x16x4_f32 v[8:11], v69, v53, v[8:11]
	v_mfma_f32_16x16x4_f32 v[8:11], v70, v54, v[8:11]
	v_mfma_f32_16x16x4_f32 v[8:11], v71, v55, v[8:11]
	global_load_dwordx4 v[32:35], v[4:5], off offset:1280
	ds_read_b128 v[48:51], v148 offset:14336
	ds_read_b128 v[52:55], v148 offset:14352
	s_waitcnt vmcnt(7)
	v_lshlrev_b32_e32 v64, 16, v36
	v_and_b32_e32 v65, 0xffff0000, v36
	v_lshlrev_b32_e32 v66, 16, v37
	v_and_b32_e32 v67, 0xffff0000, v37
	v_lshlrev_b32_e32 v68, 16, v38
	v_and_b32_e32 v69, 0xffff0000, v38
	v_lshlrev_b32_e32 v70, 16, v39
	v_and_b32_e32 v71, 0xffff0000, v39
	s_waitcnt lgkmcnt(2)
	v_mfma_f32_16x16x4_f32 v[8:11], v64, v56, v[8:11]
	v_mfma_f32_16x16x4_f32 v[8:11], v65, v57, v[8:11]
	v_mfma_f32_16x16x4_f32 v[8:11], v66, v58, v[8:11]
	v_mfma_f32_16x16x4_f32 v[8:11], v67, v59, v[8:11]
	v_mfma_f32_16x16x4_f32 v[8:11], v68, v60, v[8:11]
	v_mfma_f32_16x16x4_f32 v[8:11], v69, v61, v[8:11]
	v_mfma_f32_16x16x4_f32 v[8:11], v70, v62, v[8:11]
	v_mfma_f32_16x16x4_f32 v[8:11], v71, v63, v[8:11]
	global_load_dwordx4 v[36:39], v[4:5], off offset:1344
	ds_read_b128 v[56:59], v148 offset:15360
	ds_read_b128 v[60:63], v148 offset:15376
	s_waitcnt vmcnt(7)
	v_lshlrev_b32_e32 v64, 16, v40
	v_and_b32_e32 v65, 0xffff0000, v40
	v_lshlrev_b32_e32 v66, 16, v41
	v_and_b32_e32 v67, 0xffff0000, v41
	v_lshlrev_b32_e32 v68, 16, v42
	v_and_b32_e32 v69, 0xffff0000, v42
	v_lshlrev_b32_e32 v70, 16, v43
	v_and_b32_e32 v71, 0xffff0000, v43
	s_waitcnt lgkmcnt(2)
	v_mfma_f32_16x16x4_f32 v[8:11], v64, v48, v[8:11]
	v_mfma_f32_16x16x4_f32 v[8:11], v65, v49, v[8:11]
	v_mfma_f32_16x16x4_f32 v[8:11], v66, v50, v[8:11]
	v_mfma_f32_16x16x4_f32 v[8:11], v67, v51, v[8:11]
	v_mfma_f32_16x16x4_f32 v[8:11], v68, v52, v[8:11]
	v_mfma_f32_16x16x4_f32 v[8:11], v69, v53, v[8:11]
	v_mfma_f32_16x16x4_f32 v[8:11], v70, v54, v[8:11]
	v_mfma_f32_16x16x4_f32 v[8:11], v71, v55, v[8:11]
	global_load_dwordx4 v[40:43], v[4:5], off offset:1408
	ds_read_b128 v[48:51], v148 offset:16384
	ds_read_b128 v[52:55], v148 offset:16400
	s_waitcnt vmcnt(7)
	v_lshlrev_b32_e32 v64, 16, v44
	v_and_b32_e32 v65, 0xffff0000, v44
	v_lshlrev_b32_e32 v66, 16, v45
	v_and_b32_e32 v67, 0xffff0000, v45
	v_lshlrev_b32_e32 v68, 16, v46
	v_and_b32_e32 v69, 0xffff0000, v46
	v_lshlrev_b32_e32 v70, 16, v47
	v_and_b32_e32 v71, 0xffff0000, v47
	s_waitcnt lgkmcnt(2)
; __device__ __forceinline__ float bf2f(bfu h) { return __uint_as_float(((unsigned)h) << 16); }
; #define SHX(v, m) shx_((v), (m), lane)
; __device__ void ba_item(const Params& p, int L, int rp) {
;     ...
;   for (int bt = 0; bt < 8; ++bt) {
;     bf16x8 h0[2], h1[2]; f32x4 ps[2][4];
;     _Pragma("unroll") for (int u = 0; u < 2; ++u) {
;       const int row = rp * 128 + wid * 16 + bt * 2 + u;
;       const bfu* hr = hb + (long)row * 1024 + lane * 16;
;       h0[u] = *(const bf16x8*)hr; h1[u] = *(const bf16x8*)(hr + 8);
;       _Pragma("unroll") for (int i = 0; i < 4; ++i) ps[u][i] = *(const f32x4*)(rowss + (long)row * 16 + i * 4);
;     }
;     _Pragma("unroll") for (int u = 0; u < 2; ++u) {
;       const int row = rp * 128 + wid * 16 + bt * 2 + u;
;       float hf[16];
;       _Pragma("unroll") for (int e = 0; e < 8; ++e) { hf[e] = bf2f((bfu)h0[u][e]); hf[8 + e] = bf2f((bfu)h1[u][e]); }
;       float a[8];
;       _Pragma("unroll") for (int j = 0; j < 8; ++j) {
;         float s = 0.f;
;         _Pragma("unroll") for (int e4 = 0; e4 < 4; ++e4) _Pragma("unroll") for (int e = 0; e < 4; ++e) s += hf[e4 * 4 + e] * wr_[j][e4][e];
;         _Pragma("unroll") for (int o = 32; o >= 1; o >>= 1) s += SHX(s, o);
;         a[j] = s;
;       }
	v_mfma_f32_16x16x4_f32 v[8:11], v64, v56, v[8:11]
	v_mfma_f32_16x16x4_f32 v[8:11], v65, v57, v[8:11]
	v_mfma_f32_16x16x4_f32 v[8:11], v66, v58, v[8:11]
	v_mfma_f32_16x16x4_f32 v[8:11], v67, v59, v[8:11]
	v_mfma_f32_16x16x4_f32 v[8:11], v68, v60, v[8:11]
	v_mfma_f32_16x16x4_f32 v[8:11], v69, v61, v[8:11]
	v_mfma_f32_16x16x4_f32 v[8:11], v70, v62, v[8:11]
	v_mfma_f32_16x16x4_f32 v[8:11], v71, v63, v[8:11]
	global_load_dwordx4 v[44:47], v[4:5], off offset:1472
	ds_read_b128 v[56:59], v148 offset:17408
	ds_read_b128 v[60:63], v148 offset:17424
	s_waitcnt vmcnt(7)
	v_lshlrev_b32_e32 v64, 16, v16
	v_and_b32_e32 v65, 0xffff0000, v16
	v_lshlrev_b32_e32 v66, 16, v17
	v_and_b32_e32 v67, 0xffff0000, v17
	v_lshlrev_b32_e32 v68, 16, v18
	v_and_b32_e32 v69, 0xffff0000, v18
	v_lshlrev_b32_e32 v70, 16, v19
	v_and_b32_e32 v71, 0xffff0000, v19
	s_waitcnt lgkmcnt(2)
	v_mfma_f32_16x16x4_f32 v[8:11], v64, v48, v[8:11]
	v_mfma_f32_16x16x4_f32 v[8:11], v65, v49, v[8:11]
	v_mfma_f32_16x16x4_f32 v[8:11], v66, v50, v[8:11]
	v_mfma_f32_16x16x4_f32 v[8:11], v67, v51, v[8:11]
	v_mfma_f32_16x16x4_f32 v[8:11], v68, v52, v[8:11]
	v_mfma_f32_16x16x4_f32 v[8:11], v69, v53, v[8:11]
	v_mfma_f32_16x16x4_f32 v[8:11], v70, v54, v[8:11]
	v_mfma_f32_16x16x4_f32 v[8:11], v71, v55, v[8:11]
	global_load_dwordx4 v[16:19], v[4:5], off offset:1536
	ds_read_b128 v[48:51], v148 offset:18432
	ds_read_b128 v[52:55], v148 offset:18448
	s_waitcnt vmcnt(7)
	v_lshlrev_b32_e32 v64, 16, v20
	v_and_b32_e32 v65, 0xffff0000, v20
	v_lshlrev_b32_e32 v66, 16, v21
	v_and_b32_e32 v67, 0xffff0000, v21
	v_lshlrev_b32_e32 v68, 16, v22
	v_and_b32_e32 v69, 0xffff0000, v22
	v_lshlrev_b32_e32 v70, 16, v23
	v_and_b32_e32 v71, 0xffff0000, v23
	s_waitcnt lgkmcnt(2)
	v_mfma_f32_16x16x4_f32 v[8:11], v64, v56, v[8:11]
	v_mfma_f32_16x16x4_f32 v[8:11], v65, v57, v[8:11]
	v_mfma_f32_16x16x4_f32 v[8:11], v66, v58, v[8:11]
	v_mfma_f32_16x16x4_f32 v[8:11], v67, v59, v[8:11]
	v_mfma_f32_16x16x4_f32 v[8:11], v68, v60, v[8:11]
	v_mfma_f32_16x16x4_f32 v[8:11], v69, v61, v[8:11]
	v_mfma_f32_16x16x4_f32 v[8:11], v70, v62, v[8:11]
	v_mfma_f32_16x16x4_f32 v[8:11], v71, v63, v[8:11]
	global_load_dwordx4 v[20:23], v[4:5], off offset:1600
	ds_read_b128 v[56:59], v148 offset:19456
	ds_read_b128 v[60:63], v148 offset:19472
	s_waitcnt vmcnt(7)
	v_lshlrev_b32_e32 v64, 16, v24
	v_and_b32_e32 v65, 0xffff0000, v24
	v_lshlrev_b32_e32 v66, 16, v25
	v_and_b32_e32 v67, 0xffff0000, v25
	v_lshlrev_b32_e32 v68, 16, v26
	v_and_b32_e32 v69, 0xffff0000, v26
	v_lshlrev_b32_e32 v70, 16, v27
	v_and_b32_e32 v71, 0xffff0000, v27
	s_waitcnt lgkmcnt(2)
	v_mfma_f32_16x16x4_f32 v[8:11], v64, v48, v[8:11]
	v_mfma_f32_16x16x4_f32 v[8:11], v65, v49, v[8:11]
	v_mfma_f32_16x16x4_f32 v[8:11], v66, v50, v[8:11]
	v_mfma_f32_16x16x4_f32 v[8:11], v67, v51, v[8:11]
	v_mfma_f32_16x16x4_f32 v[8:11], v68, v52, v[8:11]
	v_mfma_f32_16x16x4_f32 v[8:11], v69, v53, v[8:11]
	v_mfma_f32_16x16x4_f32 v[8:11], v70, v54, v[8:11]
	v_mfma_f32_16x16x4_f32 v[8:11], v71, v55, v[8:11]
	global_load_dwordx4 v[24:27], v[4:5], off offset:1664
	ds_read_b128 v[48:51], v148 offset:20480
	ds_read_b128 v[52:55], v148 offset:20496
	s_waitcnt vmcnt(7)
	v_lshlrev_b32_e32 v64, 16, v28
	v_and_b32_e32 v65, 0xffff0000, v28
	v_lshlrev_b32_e32 v66, 16, v29
	v_and_b32_e32 v67, 0xffff0000, v29
	v_lshlrev_b32_e32 v68, 16, v30
	v_and_b32_e32 v69, 0xffff0000, v30
	v_lshlrev_b32_e32 v70, 16, v31
	v_and_b32_e32 v71, 0xffff0000, v31
	s_waitcnt lgkmcnt(2)
	v_mfma_f32_16x16x4_f32 v[8:11], v64, v56, v[8:11]
	v_mfma_f32_16x16x4_f32 v[8:11], v65, v57, v[8:11]
	v_mfma_f32_16x16x4_f32 v[8:11], v66, v58, v[8:11]
	v_mfma_f32_16x16x4_f32 v[8:11], v67, v59, v[8:11]
	v_mfma_f32_16x16x4_f32 v[8:11], v68, v60, v[8:11]
	v_mfma_f32_16x16x4_f32 v[8:11], v69, v61, v[8:11]
	v_mfma_f32_16x16x4_f32 v[8:11], v70, v62, v[8:11]
	v_mfma_f32_16x16x4_f32 v[8:11], v71, v63, v[8:11]
	global_load_dwordx4 v[28:31], v[4:5], off offset:1728
	ds_read_b128 v[56:59], v148 offset:21504
	ds_read_b128 v[60:63], v148 offset:21520
	s_waitcnt vmcnt(7)
	v_lshlrev_b32_e32 v64, 16, v32
	v_and_b32_e32 v65, 0xffff0000, v32
	v_lshlrev_b32_e32 v66, 16, v33
	v_and_b32_e32 v67, 0xffff0000, v33
	v_lshlrev_b32_e32 v68, 16, v34
	v_and_b32_e32 v69, 0xffff0000, v34
	v_lshlrev_b32_e32 v70, 16, v35
	v_and_b32_e32 v71, 0xffff0000, v35
	s_waitcnt lgkmcnt(2)
	v_mfma_f32_16x16x4_f32 v[8:11], v64, v48, v[8:11]
	v_mfma_f32_16x16x4_f32 v[8:11], v65, v49, v[8:11]
	v_mfma_f32_16x16x4_f32 v[8:11], v66, v50, v[8:11]
	v_mfma_f32_16x16x4_f32 v[8:11], v67, v51, v[8:11]
	v_mfma_f32_16x16x4_f32 v[8:11], v68, v52, v[8:11]
	v_mfma_f32_16x16x4_f32 v[8:11], v69, v53, v[8:11]
	v_mfma_f32_16x16x4_f32 v[8:11], v70, v54, v[8:11]
	v_mfma_f32_16x16x4_f32 v[8:11], v71, v55, v[8:11]
	global_load_dwordx4 v[32:35], v[4:5], off offset:1792
	ds_read_b128 v[48:51], v148 offset:22528
	ds_read_b128 v[52:55], v148 offset:22544
	s_waitcnt vmcnt(7)
	v_lshlrev_b32_e32 v64, 16, v36
	v_and_b32_e32 v65, 0xffff0000, v36
	v_lshlrev_b32_e32 v66, 16, v37
	v_and_b32_e32 v67, 0xffff0000, v37
	v_lshlrev_b32_e32 v68, 16, v38
	v_and_b32_e32 v69, 0xffff0000, v38
	v_lshlrev_b32_e32 v70, 16, v39
	v_and_b32_e32 v71, 0xffff0000, v39
	s_waitcnt lgkmcnt(2)
	v_mfma_f32_16x16x4_f32 v[8:11], v64, v56, v[8:11]
	v_mfma_f32_16x16x4_f32 v[8:11], v65, v57, v[8:11]
	v_mfma_f32_16x16x4_f32 v[8:11], v66, v58, v[8:11]
	v_mfma_f32_16x16x4_f32 v[8:11], v67, v59, v[8:11]
	v_mfma_f32_16x16x4_f32 v[8:11], v68, v60, v[8:11]
	v_mfma_f32_16x16x4_f32 v[8:11], v69, v61, v[8:11]
	v_mfma_f32_16x16x4_f32 v[8:11], v70, v62, v[8:11]
	v_mfma_f32_16x16x4_f32 v[8:11], v71, v63, v[8:11]
	global_load_dwordx4 v[36:39], v[4:5], off offset:1856
	ds_read_b128 v[56:59], v148 offset:23552
	ds_read_b128 v[60:63], v148 offset:23568
	s_waitcnt vmcnt(7)
; __device__ __forceinline__ float bf2f(bfu h) { return __uint_as_float(((unsigned)h) << 16); }
; #define SHX(v, m) shx_((v), (m), lane)
; __device__ void ba_item(const Params& p, int L, int rp) {
;     ...
;   for (int bt = 0; bt < 8; ++bt) {
;     bf16x8 h0[2], h1[2]; f32x4 ps[2][4];
;     _Pragma("unroll") for (int u = 0; u < 2; ++u) {
;       const int row = rp * 128 + wid * 16 + bt * 2 + u;
;       const bfu* hr = hb + (long)row * 1024 + lane * 16;
;       h0[u] = *(const bf16x8*)hr; h1[u] = *(const bf16x8*)(hr + 8);
;       _Pragma("unroll") for (int i = 0; i < 4; ++i) ps[u][i] = *(const f32x4*)(rowss + (long)row * 16 + i * 4);
;     }
;     _Pragma("unroll") for (int u = 0; u < 2; ++u) {
;       const int row = rp * 128 + wid * 16 + bt * 2 + u;
;       float hf[16];
;       _Pragma("unroll") for (int e = 0; e < 8; ++e) { hf[e] = bf2f((bfu)h0[u][e]); hf[8 + e] = bf2f((bfu)h1[u][e]); }
;       float a[8];
;       _Pragma("unroll") for (int j = 0; j < 8; ++j) {
;         float s = 0.f;
;         _Pragma("unroll") for (int e4 = 0; e4 < 4; ++e4) _Pragma("unroll") for (int e = 0; e < 4; ++e) s += hf[e4 * 4 + e] * wr_[j][e4][e];
;         _Pragma("unroll") for (int o = 32; o >= 1; o >>= 1) s += SHX(s, o);
;         a[j] = s;
;       }
	v_lshlrev_b32_e32 v64, 16, v40
	v_and_b32_e32 v65, 0xffff0000, v40
	v_lshlrev_b32_e32 v66, 16, v41
	v_and_b32_e32 v67, 0xffff0000, v41
	v_lshlrev_b32_e32 v68, 16, v42
	v_and_b32_e32 v69, 0xffff0000, v42
	v_lshlrev_b32_e32 v70, 16, v43
	v_and_b32_e32 v71, 0xffff0000, v43
	s_waitcnt lgkmcnt(2)
	v_mfma_f32_16x16x4_f32 v[8:11], v64, v48, v[8:11]
	v_mfma_f32_16x16x4_f32 v[8:11], v65, v49, v[8:11]
	v_mfma_f32_16x16x4_f32 v[8:11], v66, v50, v[8:11]
	v_mfma_f32_16x16x4_f32 v[8:11], v67, v51, v[8:11]
	v_mfma_f32_16x16x4_f32 v[8:11], v68, v52, v[8:11]
	v_mfma_f32_16x16x4_f32 v[8:11], v69, v53, v[8:11]
	v_mfma_f32_16x16x4_f32 v[8:11], v70, v54, v[8:11]
	v_mfma_f32_16x16x4_f32 v[8:11], v71, v55, v[8:11]
	global_load_dwordx4 v[40:43], v[4:5], off offset:1920
	ds_read_b128 v[48:51], v148 offset:24576
	ds_read_b128 v[52:55], v148 offset:24592
	s_waitcnt vmcnt(7)
	v_lshlrev_b32_e32 v64, 16, v44
	v_and_b32_e32 v65, 0xffff0000, v44
	v_lshlrev_b32_e32 v66, 16, v45
	v_and_b32_e32 v67, 0xffff0000, v45
	v_lshlrev_b32_e32 v68, 16, v46
	v_and_b32_e32 v69, 0xffff0000, v46
	v_lshlrev_b32_e32 v70, 16, v47
	v_and_b32_e32 v71, 0xffff0000, v47
	s_waitcnt lgkmcnt(2)
	v_mfma_f32_16x16x4_f32 v[8:11], v64, v56, v[8:11]
	v_mfma_f32_16x16x4_f32 v[8:11], v65, v57, v[8:11]
	v_mfma_f32_16x16x4_f32 v[8:11], v66, v58, v[8:11]
	v_mfma_f32_16x16x4_f32 v[8:11], v67, v59, v[8:11]
	v_mfma_f32_16x16x4_f32 v[8:11], v68, v60, v[8:11]
	v_mfma_f32_16x16x4_f32 v[8:11], v69, v61, v[8:11]
	v_mfma_f32_16x16x4_f32 v[8:11], v70, v62, v[8:11]
	v_mfma_f32_16x16x4_f32 v[8:11], v71, v63, v[8:11]
	global_load_dwordx4 v[44:47], v[4:5], off offset:1984
	ds_read_b128 v[56:59], v148 offset:25600
	ds_read_b128 v[60:63], v148 offset:25616
	s_waitcnt vmcnt(7)
	v_lshlrev_b32_e32 v64, 16, v16
	v_and_b32_e32 v65, 0xffff0000, v16
	v_lshlrev_b32_e32 v66, 16, v17
	v_and_b32_e32 v67, 0xffff0000, v17
	v_lshlrev_b32_e32 v68, 16, v18
	v_and_b32_e32 v69, 0xffff0000, v18
	v_lshlrev_b32_e32 v70, 16, v19
	v_and_b32_e32 v71, 0xffff0000, v19
	s_waitcnt lgkmcnt(2)
	v_mfma_f32_16x16x4_f32 v[8:11], v64, v48, v[8:11]
	v_mfma_f32_16x16x4_f32 v[8:11], v65, v49, v[8:11]
	v_mfma_f32_16x16x4_f32 v[8:11], v66, v50, v[8:11]
	v_mfma_f32_16x16x4_f32 v[8:11], v67, v51, v[8:11]
	v_mfma_f32_16x16x4_f32 v[8:11], v68, v52, v[8:11]
	v_mfma_f32_16x16x4_f32 v[8:11], v69, v53, v[8:11]
	v_mfma_f32_16x16x4_f32 v[8:11], v70, v54, v[8:11]
	v_mfma_f32_16x16x4_f32 v[8:11], v71, v55, v[8:11]
	ds_read_b128 v[48:51], v148 offset:26624
	ds_read_b128 v[52:55], v148 offset:26640
	s_waitcnt vmcnt(6)
	v_lshlrev_b32_e32 v64, 16, v20
	v_and_b32_e32 v65, 0xffff0000, v20
	v_lshlrev_b32_e32 v66, 16, v21
	v_and_b32_e32 v67, 0xffff0000, v21
	v_lshlrev_b32_e32 v68, 16, v22
	v_and_b32_e32 v69, 0xffff0000, v22
	v_lshlrev_b32_e32 v70, 16, v23
	v_and_b32_e32 v71, 0xffff0000, v23
	s_waitcnt lgkmcnt(2)
	v_mfma_f32_16x16x4_f32 v[8:11], v64, v56, v[8:11]
	v_mfma_f32_16x16x4_f32 v[8:11], v65, v57, v[8:11]
	v_mfma_f32_16x16x4_f32 v[8:11], v66, v58, v[8:11]
	v_mfma_f32_16x16x4_f32 v[8:11], v67, v59, v[8:11]
	v_mfma_f32_16x16x4_f32 v[8:11], v68, v60, v[8:11]
	v_mfma_f32_16x16x4_f32 v[8:11], v69, v61, v[8:11]
	v_mfma_f32_16x16x4_f32 v[8:11], v70, v62, v[8:11]
	v_mfma_f32_16x16x4_f32 v[8:11], v71, v63, v[8:11]
	ds_read_b128 v[56:59], v148 offset:27648
	ds_read_b128 v[60:63], v148 offset:27664
	s_waitcnt vmcnt(5)
	v_lshlrev_b32_e32 v64, 16, v24
	v_and_b32_e32 v65, 0xffff0000, v24
	v_lshlrev_b32_e32 v66, 16, v25
	v_and_b32_e32 v67, 0xffff0000, v25
	v_lshlrev_b32_e32 v68, 16, v26
	v_and_b32_e32 v69, 0xffff0000, v26
	v_lshlrev_b32_e32 v70, 16, v27
	v_and_b32_e32 v71, 0xffff0000, v27
	s_waitcnt lgkmcnt(2)
	v_mfma_f32_16x16x4_f32 v[8:11], v64, v48, v[8:11]
	v_mfma_f32_16x16x4_f32 v[8:11], v65, v49, v[8:11]
	v_mfma_f32_16x16x4_f32 v[8:11], v66, v50, v[8:11]
	v_mfma_f32_16x16x4_f32 v[8:11], v67, v51, v[8:11]
	v_mfma_f32_16x16x4_f32 v[8:11], v68, v52, v[8:11]
	v_mfma_f32_16x16x4_f32 v[8:11], v69, v53, v[8:11]
	v_mfma_f32_16x16x4_f32 v[8:11], v70, v54, v[8:11]
	v_mfma_f32_16x16x4_f32 v[8:11], v71, v55, v[8:11]
	ds_read_b128 v[48:51], v148 offset:28672
	ds_read_b128 v[52:55], v148 offset:28688
	s_waitcnt vmcnt(4)
	v_lshlrev_b32_e32 v64, 16, v28
	v_and_b32_e32 v65, 0xffff0000, v28
	v_lshlrev_b32_e32 v66, 16, v29
	v_and_b32_e32 v67, 0xffff0000, v29
	v_lshlrev_b32_e32 v68, 16, v30
	v_and_b32_e32 v69, 0xffff0000, v30
	v_lshlrev_b32_e32 v70, 16, v31
	v_and_b32_e32 v71, 0xffff0000, v31
	s_waitcnt lgkmcnt(2)
	v_mfma_f32_16x16x4_f32 v[8:11], v64, v56, v[8:11]
	v_mfma_f32_16x16x4_f32 v[8:11], v65, v57, v[8:11]
	v_mfma_f32_16x16x4_f32 v[8:11], v66, v58, v[8:11]
	v_mfma_f32_16x16x4_f32 v[8:11], v67, v59, v[8:11]
	v_mfma_f32_16x16x4_f32 v[8:11], v68, v60, v[8:11]
	v_mfma_f32_16x16x4_f32 v[8:11], v69, v61, v[8:11]
	v_mfma_f32_16x16x4_f32 v[8:11], v70, v62, v[8:11]
	v_mfma_f32_16x16x4_f32 v[8:11], v71, v63, v[8:11]
	ds_read_b128 v[56:59], v148 offset:29696
	ds_read_b128 v[60:63], v148 offset:29712
	s_waitcnt vmcnt(3)
	v_lshlrev_b32_e32 v64, 16, v32
	v_and_b32_e32 v65, 0xffff0000, v32
	v_lshlrev_b32_e32 v66, 16, v33
	v_and_b32_e32 v67, 0xffff0000, v33
	v_lshlrev_b32_e32 v68, 16, v34
	v_and_b32_e32 v69, 0xffff0000, v34
	v_lshlrev_b32_e32 v70, 16, v35
	v_and_b32_e32 v71, 0xffff0000, v35
	s_waitcnt lgkmcnt(2)
	v_mfma_f32_16x16x4_f32 v[8:11], v64, v48, v[8:11]
	v_mfma_f32_16x16x4_f32 v[8:11], v65, v49, v[8:11]
	v_mfma_f32_16x16x4_f32 v[8:11], v66, v50, v[8:11]
	v_mfma_f32_16x16x4_f32 v[8:11], v67, v51, v[8:11]
	v_mfma_f32_16x16x4_f32 v[8:11], v68, v52, v[8:11]
	v_mfma_f32_16x16x4_f32 v[8:11], v69, v53, v[8:11]
	v_mfma_f32_16x16x4_f32 v[8:11], v70, v54, v[8:11]
	v_mfma_f32_16x16x4_f32 v[8:11], v71, v55, v[8:11]
	ds_read_b128 v[48:51], v148 offset:30720
	ds_read_b128 v[52:55], v148 offset:30736
	s_waitcnt vmcnt(2)
; __device__ __forceinline__ float bf2f(bfu h) { return __uint_as_float(((unsigned)h) << 16); }
; #define SHX(v, m) shx_((v), (m), lane)
; __device__ void ba_item(const Params& p, int L, int rp) {
;     ...
;   for (int bt = 0; bt < 8; ++bt) {
;     bf16x8 h0[2], h1[2]; f32x4 ps[2][4];
;     _Pragma("unroll") for (int u = 0; u < 2; ++u) {
;       const int row = rp * 128 + wid * 16 + bt * 2 + u;
;       const bfu* hr = hb + (long)row * 1024 + lane * 16;
;       h0[u] = *(const bf16x8*)hr; h1[u] = *(const bf16x8*)(hr + 8);
;       _Pragma("unroll") for (int i = 0; i < 4; ++i) ps[u][i] = *(const f32x4*)(rowss + (long)row * 16 + i * 4);
;     }
;     _Pragma("unroll") for (int u = 0; u < 2; ++u) {
;       const int row = rp * 128 + wid * 16 + bt * 2 + u;
;       float hf[16];
;       _Pragma("unroll") for (int e = 0; e < 8; ++e) { hf[e] = bf2f((bfu)h0[u][e]); hf[8 + e] = bf2f((bfu)h1[u][e]); }
;       float a[8];
;       _Pragma("unroll") for (int j = 0; j < 8; ++j) {
;         float s = 0.f;
;         _Pragma("unroll") for (int e4 = 0; e4 < 4; ++e4) _Pragma("unroll") for (int e = 0; e < 4; ++e) s += hf[e4 * 4 + e] * wr_[j][e4][e];
;         _Pragma("unroll") for (int o = 32; o >= 1; o >>= 1) s += SHX(s, o);
;         a[j] = s;
;       }
	v_lshlrev_b32_e32 v64, 16, v36
	v_and_b32_e32 v65, 0xffff0000, v36
	v_lshlrev_b32_e32 v66, 16, v37
	v_and_b32_e32 v67, 0xffff0000, v37
	v_lshlrev_b32_e32 v68, 16, v38
	v_and_b32_e32 v69, 0xffff0000, v38
	v_lshlrev_b32_e32 v70, 16, v39
	v_and_b32_e32 v71, 0xffff0000, v39
	s_waitcnt lgkmcnt(2)
	v_mfma_f32_16x16x4_f32 v[8:11], v64, v56, v[8:11]
	v_mfma_f32_16x16x4_f32 v[8:11], v65, v57, v[8:11]
	v_mfma_f32_16x16x4_f32 v[8:11], v66, v58, v[8:11]
	v_mfma_f32_16x16x4_f32 v[8:11], v67, v59, v[8:11]
	v_mfma_f32_16x16x4_f32 v[8:11], v68, v60, v[8:11]
	v_mfma_f32_16x16x4_f32 v[8:11], v69, v61, v[8:11]
	v_mfma_f32_16x16x4_f32 v[8:11], v70, v62, v[8:11]
	v_mfma_f32_16x16x4_f32 v[8:11], v71, v63, v[8:11]
	ds_read_b128 v[56:59], v148 offset:31744
	ds_read_b128 v[60:63], v148 offset:31760
	s_waitcnt vmcnt(1)
	v_lshlrev_b32_e32 v64, 16, v40
	v_and_b32_e32 v65, 0xffff0000, v40
	v_lshlrev_b32_e32 v66, 16, v41
	v_and_b32_e32 v67, 0xffff0000, v41
	v_lshlrev_b32_e32 v68, 16, v42
	v_and_b32_e32 v69, 0xffff0000, v42
	v_lshlrev_b32_e32 v70, 16, v43
	v_and_b32_e32 v71, 0xffff0000, v43
	s_waitcnt lgkmcnt(2)
	v_mfma_f32_16x16x4_f32 v[8:11], v64, v48, v[8:11]
	v_mfma_f32_16x16x4_f32 v[8:11], v65, v49, v[8:11]
	v_mfma_f32_16x16x4_f32 v[8:11], v66, v50, v[8:11]
	v_mfma_f32_16x16x4_f32 v[8:11], v67, v51, v[8:11]
	v_mfma_f32_16x16x4_f32 v[8:11], v68, v52, v[8:11]
	v_mfma_f32_16x16x4_f32 v[8:11], v69, v53, v[8:11]
	v_mfma_f32_16x16x4_f32 v[8:11], v70, v54, v[8:11]
	v_mfma_f32_16x16x4_f32 v[8:11], v71, v55, v[8:11]
	s_waitcnt vmcnt(0)
	v_lshlrev_b32_e32 v64, 16, v44
	v_and_b32_e32 v65, 0xffff0000, v44
	v_lshlrev_b32_e32 v66, 16, v45
	v_and_b32_e32 v67, 0xffff0000, v45
	v_lshlrev_b32_e32 v68, 16, v46
	v_and_b32_e32 v69, 0xffff0000, v46
	v_lshlrev_b32_e32 v70, 16, v47
	v_and_b32_e32 v71, 0xffff0000, v47
	s_waitcnt lgkmcnt(0)
; __device__ __forceinline__ float fexp(float x) { return __builtin_amdgcn_exp2f(x * 1.4426950408889634f); }
; __device__ __forceinline__ float flog(float x) { return __builtin_amdgcn_logf(x) * 0.6931471805599453f; }
; __device__ __forceinline__ float frsq(float x) { return __builtin_amdgcn_rsqf(x); }
; __device__ __forceinline__ float sigmoidf_(float x) { return frcp(1.0f + fexp(-x)); }
; __device__ void ba_item(const Params& p, int L, int rp) {
;     ...
;       if (lane < 8) {
;         float s16 = 0.f;
;         _Pragma("unroll") for (int i = 0; i < 4; ++i) s16 += (ps[u][i][0] + ps[u][i][1]) + (ps[u][i][2] + ps[u][i][3]);
;         float rs = frsq(s16 * (1.0f / 1024.0f) + 1e-6f);
;         float v = 0.f;
;         _Pragma("unroll") for (int j = 0; j < 8; ++j) if (lane == j) v = a[j];
;         v *= rs;
;         float r;
;         if (lane < 4) r = sigmoidf_(v);
;         else {
;           int hh = lane - 4;
;           float z = v + p.dn_dt_bias[(L >> 1) * 4 + hh];
;           float sp = (z > 20.f) ? z : flog(1.0f + fexp(z));
;           r = -fexp(p.dn_a_log[(L >> 1) * 4 + hh]) * sp;
;         }
;         miscw[MF_BG + (long)row * 8 + lane] = r;
;       }
	v_mfma_f32_16x16x4_f32 v[8:11], v64, v56, v[8:11]
	v_mfma_f32_16x16x4_f32 v[8:11], v65, v57, v[8:11]
	v_mfma_f32_16x16x4_f32 v[8:11], v66, v58, v[8:11]
	v_mfma_f32_16x16x4_f32 v[8:11], v67, v59, v[8:11]
	v_mfma_f32_16x16x4_f32 v[8:11], v68, v60, v[8:11]
	v_mfma_f32_16x16x4_f32 v[8:11], v69, v61, v[8:11]
	v_mfma_f32_16x16x4_f32 v[8:11], v70, v62, v[8:11]
	v_mfma_f32_16x16x4_f32 v[8:11], v71, v63, v[8:11]
	v_cmp_gt_u32_e32 vcc, 8, v2
	s_and_saveexec_b64 s[12:13], vcc
	s_nop 4
	v_add_f32_e32 v72, v72, v73
	v_add_f32_e32 v74, v74, v75
	v_add_f32_e32 v72, v72, v74
	v_add_f32_e32 v76, v76, v77
	v_add_f32_e32 v78, v78, v79
	v_add_f32_e32 v76, v76, v78
	v_add_f32_e32 v80, v80, v81
	v_add_f32_e32 v82, v82, v83
	v_add_f32_e32 v80, v80, v82
	v_add_f32_e32 v84, v84, v85
	v_add_f32_e32 v86, v86, v87
	v_add_f32_e32 v84, v84, v86
	v_add_f32_e32 v72, 0, v72
	v_add_f32_e32 v72, v76, v72
	v_add_f32_e32 v72, v80, v72
	v_add_f32_e32 v72, v84, v72
	v_fmamk_f32 v72, v72, 0x3a800000, v201
	v_rsq_f32_e32 v72, v72
	s_nop 0
	v_mul_f32_e32 v144, v8, v72
	v_mul_f32_e32 v145, 0xbfb8aa3b, v144
	v_exp_f32_e32 v145, v145
	s_nop 0
	v_add_f32_e32 v145, 1.0, v145
	v_rcp_f32_e32 v145, v145
	v_add_f32_e32 v146, v144, v142
	v_mul_f32_e32 v147, 0x3fb8aa3b, v146
	v_exp_f32_e32 v147, v147
	v_cmp_lt_f32_e64 s[0:1], s57, v146
	v_add_f32_e32 v147, 1.0, v147
	v_log_f32_e32 v147, v147
	s_nop 0
	v_mul_f32_e32 v147, 0x3f317218, v147
	v_cndmask_b32_e64 v146, v147, v146, s[0:1]
	v_mul_f32_e32 v147, 0x3fb8aa3b, v143
	v_exp_f32_e32 v147, v147
	s_nop 0
	v_mul_f32_e64 v146, v146, -v147
	v_cmp_gt_u32_e64 s[0:1], 4, v138
	s_nop 1
	v_cndmask_b32_e64 v146, v146, v145, s[0:1]
	global_store_dword v[140:141], v146, off offset:0
	v_add_f32_e32 v88, v88, v89
	v_add_f32_e32 v90, v90, v91
	v_add_f32_e32 v88, v88, v90
	v_add_f32_e32 v92, v92, v93
	v_add_f32_e32 v94, v94, v95
	v_add_f32_e32 v92, v92, v94
	v_add_f32_e32 v96, v96, v97
	v_add_f32_e32 v98, v98, v99
	v_add_f32_e32 v96, v96, v98
	v_add_f32_e32 v100, v100, v101
	v_add_f32_e32 v102, v102, v103
	v_add_f32_e32 v100, v100, v102
	v_add_f32_e32 v88, 0, v88
	v_add_f32_e32 v88, v92, v88
	v_add_f32_e32 v88, v96, v88
	v_add_f32_e32 v88, v100, v88
	v_fmamk_f32 v88, v88, 0x3a800000, v201
	v_rsq_f32_e32 v88, v88
	s_nop 0
	v_mul_f32_e32 v144, v9, v88
	v_mul_f32_e32 v145, 0xbfb8aa3b, v144
	v_exp_f32_e32 v145, v145
	s_nop 0
	v_add_f32_e32 v145, 1.0, v145
	v_rcp_f32_e32 v145, v145
	v_add_f32_e32 v146, v144, v142
	v_mul_f32_e32 v147, 0x3fb8aa3b, v146
	v_exp_f32_e32 v147, v147
	v_cmp_lt_f32_e64 s[0:1], s57, v146
	v_add_f32_e32 v147, 1.0, v147
	v_log_f32_e32 v147, v147
	s_nop 0
	v_mul_f32_e32 v147, 0x3f317218, v147
	v_cndmask_b32_e64 v146, v147, v146, s[0:1]
	v_mul_f32_e32 v147, 0x3fb8aa3b, v143
	v_exp_f32_e32 v147, v147
	s_nop 0
	v_mul_f32_e64 v146, v146, -v147
	v_cmp_gt_u32_e64 s[0:1], 4, v138
	s_nop 1
	v_cndmask_b32_e64 v146, v146, v145, s[0:1]
	global_store_dword v[140:141], v146, off offset:32
	v_add_f32_e32 v104, v104, v105
	v_add_f32_e32 v106, v106, v107
	v_add_f32_e32 v104, v104, v106
	v_add_f32_e32 v108, v108, v109
	v_add_f32_e32 v110, v110, v111
	v_add_f32_e32 v108, v108, v110
	v_add_f32_e32 v112, v112, v113
	v_add_f32_e32 v114, v114, v115
	v_add_f32_e32 v112, v112, v114
	v_add_f32_e32 v116, v116, v117
	v_add_f32_e32 v118, v118, v119
	v_add_f32_e32 v116, v116, v118
	v_add_f32_e32 v104, 0, v104
	v_add_f32_e32 v104, v108, v104
	v_add_f32_e32 v104, v112, v104
	v_add_f32_e32 v104, v116, v104
	v_fmamk_f32 v104, v104, 0x3a800000, v201
	v_rsq_f32_e32 v104, v104
	s_nop 0
	v_mul_f32_e32 v144, v10, v104
	v_mul_f32_e32 v145, 0xbfb8aa3b, v144
	v_exp_f32_e32 v145, v145
	s_nop 0
	v_add_f32_e32 v145, 1.0, v145
	v_rcp_f32_e32 v145, v145
	v_add_f32_e32 v146, v144, v142
	v_mul_f32_e32 v147, 0x3fb8aa3b, v146
	v_exp_f32_e32 v147, v147
	v_cmp_lt_f32_e64 s[0:1], s57, v146
	v_add_f32_e32 v147, 1.0, v147
	v_log_f32_e32 v147, v147
	s_nop 0
	v_mul_f32_e32 v147, 0x3f317218, v147
	v_cndmask_b32_e64 v146, v147, v146, s[0:1]
	v_mul_f32_e32 v147, 0x3fb8aa3b, v143
	v_exp_f32_e32 v147, v147
	s_nop 0
	v_mul_f32_e64 v146, v146, -v147
	v_cmp_gt_u32_e64 s[0:1], 4, v138
	s_nop 1
	v_cndmask_b32_e64 v146, v146, v145, s[0:1]
	global_store_dword v[140:141], v146, off offset:64
	v_add_f32_e32 v120, v120, v121
	v_add_f32_e32 v122, v122, v123
	v_add_f32_e32 v120, v120, v122
	v_add_f32_e32 v124, v124, v125
	v_add_f32_e32 v126, v126, v127
	v_add_f32_e32 v124, v124, v126
	v_add_f32_e32 v128, v128, v129
	v_add_f32_e32 v130, v130, v131
	v_add_f32_e32 v128, v128, v130
	v_add_f32_e32 v132, v132, v133
	v_add_f32_e32 v134, v134, v135
	v_add_f32_e32 v132, v132, v134
	v_add_f32_e32 v120, 0, v120
	v_add_f32_e32 v120, v124, v120
	v_add_f32_e32 v120, v128, v120
	v_add_f32_e32 v120, v132, v120
	v_fmamk_f32 v120, v120, 0x3a800000, v201
	v_rsq_f32_e32 v120, v120
	s_nop 0
	v_mul_f32_e32 v144, v11, v120
	v_mul_f32_e32 v145, 0xbfb8aa3b, v144
	v_exp_f32_e32 v145, v145
	s_nop 0
	v_add_f32_e32 v145, 1.0, v145
	v_rcp_f32_e32 v145, v145
	v_add_f32_e32 v146, v144, v142
	v_mul_f32_e32 v147, 0x3fb8aa3b, v146
	v_exp_f32_e32 v147, v147
	v_cmp_lt_f32_e64 s[0:1], s57, v146
	v_add_f32_e32 v147, 1.0, v147
	v_log_f32_e32 v147, v147
	s_nop 0
	v_mul_f32_e32 v147, 0x3f317218, v147
	v_cndmask_b32_e64 v146, v147, v146, s[0:1]
	v_mul_f32_e32 v147, 0x3fb8aa3b, v143
	v_exp_f32_e32 v147, v147
	s_nop 0
	v_mul_f32_e64 v146, v146, -v147
	v_cmp_gt_u32_e64 s[0:1], 4, v138
	s_nop 1
	v_cndmask_b32_e64 v146, v146, v145, s[0:1]
	global_store_dword v[140:141], v146, off offset:96
	s_or_b64 exec, exec, s[12:13]
	s_barrier
	s_branch .LBB0_627
